# speedup vs baseline: 1.0312x; 1.0039x over previous
; DEV int tid_opaque() { int t = threadIdx.x; asm volatile("" : "+v"(t)); return t; }
; template <bool SB> ...
;     const int t = tid_opaque(), lane = t & 63, wid = t >> 6, fr = lane & 15, fq = lane >> 4;
;     char* sK = smem; char* sV = smem + 8192; float* sF = (float*)(smem + 16384);
;     const int qw0 = wid * 32;
;     const bool wave_valid = qw0 < nq;
;     bf16x8 qf[2][2]; int kmax[2]; float fqv[2]; bool rvalid[2];
; #pragma unroll
;     for (int qt = 0; qt < 2; ++qt) {
;         const int qi = qw0 + qt * 16 + fr, qc = min(qi, nq - 1);
; #pragma unroll
;         for (int kk = 0; kk < 2; ++kk) qf[qt][kk] = *(const bf16x8*)(Q + (size_t)qc * ldq + kk * 32 + fq * 8);
;         rvalid[qt] = qi < nq;
;         kmax[qt] = rvalid[qt] ? q_pos0 + qi - (SB ? 1 : 0) : -1;
;         fqv[qt] = SB ? 0.f : Fq[qc] * LOG2E;
;     }
;     const int wave_kmax = wave_valid ? q_pos0 + min(qw0 + 31, nq - 1) - (SB ? 1 : 0) : -1;
;     const int kt_hi = (q_pos0 + nq - 1) >> 6;
;     f32x4 o[4][2];
; #pragma unroll
;     for (int a = 0; a < 4; ++a) { o[a][0] = (f32x4){0.f, 0.f, 0.f, 0.f}; o[a][1] = (f32x4){0.f, 0.f, 0.f, 0.f}; }
;     float m[2] = {-1e30f, -1e30f}, ls[2] = {SB ? 1.f : 0.f, SB ? 1.f : 0.f};
;     const int srow = t >> 2, sch = (t & 3) * 2;
;     uint4 rk0, rk1, rv0, rv1; float rf = 0.f;
;     {
;         const size_t kb = (size_t)kt_hi * 64;
;         const bf16_t* kp = Kp + (kb + srow) * ldk + sch * 8; rk0 = *(const uint4*)kp; rk1 = *(const uint4*)(kp + 8);
;         const bf16_t* vp = VT + (size_t)srow * ldvt + kb + sch * 8; rv0 = *(const uint4*)vp; rv1 = *(const uint4*)(vp + 8);
;         if (!SB && t < 64) rf = Fk[kb + t];
;     }
;     const int so0 = srow * 128 + ((sch ^ (srow & 7)) << 4), so1 = srow * 128 + (((sch + 1) ^ (srow & 7)) << 4);
;     const int sw = fr & 7;
;     volatile int* xflag = (volatile int*)(smem + 16384 + 256);
;     if (t < 4) xflag[t] = 0;
.LBB0_1683:
	v_readlane_b32 s13, v250, 53
	s_lshl_b32 s4, s12, 6
	s_ashr_i32 s5, s4, 31
	s_lshl_b64 s[2:3], s[4:5], 1
	s_add_u32 s0, s0, s2
	s_addc_u32 s1, s1, s3
	s_ashr_i32 s47, s46, 31
	s_lshl_b64 s[4:5], s[46:47], 9
	s_add_u32 s4, s29, s4
	s_addc_u32 s5, s30, s5
	s_add_u32 s4, s4, s2
	v_mov_b32_e32 v68, v186
	v_writelane_b32 v254, s2, 39
	s_addc_u32 s5, s5, s3
	s_add_i32 s11, s9, -1
	v_and_b32_e32 v32, 48, v68
	v_ashrrev_i32_e32 v69, 6, v68
	v_lshl_add_u64 v[8:9], s[4:5], 0, v[32:33]
	s_add_i32 s4, s11, s10
	v_and_b32_e32 v70, 15, v68
	v_lshlrev_b32_e32 v71, 5, v69
	s_ashr_i32 s4, s4, 6
	v_or_b32_e32 v98, v71, v70
	v_ashrrev_i32_e32 v100, 2, v68
	s_ashr_i32 s5, s4, 31
	v_or_b32_e32 v96, 16, v98
	v_lshlrev_b32_e32 v16, 1, v68
	s_lshl_b64 s[12:13], s[4:5], 6
	v_ashrrev_i32_e32 v101, 31, v100
	v_min_i32_e32 v0, s11, v98
	v_min_i32_e32 v10, s11, v96
	v_and_b32_e32 v72, 6, v16
	v_lshl_add_u64 v[16:17], s[12:13], 0, v[100:101]
	v_mad_i64_i32 v[24:25], s[12:13], s8, v100, 0
	v_ashrrev_i32_e32 v1, 31, v0
	v_ashrrev_i32_e32 v11, 31, v10
	v_lshlrev_b64 v[16:17], 9, v[16:17]
	v_lshl_add_u64 v[66:67], v[24:25], 1, s[6:7]
	s_lshl_b64 s[6:7], s[4:5], 7
	v_lshlrev_b64 v[0:1], 9, v[0:1]
	v_lshlrev_b64 v[10:11], 9, v[10:11]
	v_lshl_add_u64 v[16:17], s[0:1], 0, v[16:17]
	v_lshlrev_b32_e32 v32, 4, v72
	v_lshl_add_u64 v[24:25], v[66:67], 0, s[6:7]
	v_lshl_add_u64 v[4:5], v[8:9], 0, v[0:1]
	v_lshl_add_u64 v[12:13], v[8:9], 0, v[10:11]
	v_lshl_add_u64 v[20:21], v[16:17], 0, v[32:33]
	v_lshl_add_u64 v[28:29], v[24:25], 0, v[32:33]
	flat_load_dwordx4 v[0:3], v[4:5]
	s_nop 0
	flat_load_dwordx4 v[4:7], v[4:5] offset:64
	s_nop 0
	flat_load_dwordx4 v[8:11], v[12:13]
	s_nop 0
	flat_load_dwordx4 v[12:15], v[12:13] offset:64
	s_nop 0
	flat_load_dwordx4 v[16:19], v[20:21]
	s_nop 0
	flat_load_dwordx4 v[20:23], v[20:21] offset:16
	s_nop 0
	flat_load_dwordx4 v[24:27], v[28:29]
	s_nop 0
	flat_load_dwordx4 v[28:31], v[28:29] offset:16
	v_writelane_b32 v254, s3, 40
	v_cmp_gt_i32_e32 vcc, 4, v68
	s_and_saveexec_b64 s[6:7], vcc
	s_cbranch_execz .LBB0_1685
	s_mov_b64 s[12:13], src_shared_base
	v_lshl_add_u32 v32, v68, 2, 0
	v_add_u32_e32 v34, 0x4100, v32
	v_mov_b32_e32 v35, s13
	ds_write_b32 v34, v33
	s_waitcnt vmcnt(0) lgkmcnt(0)

; template <bool SB> ...
;     ...
;         __syncthreads();
;         if (early && (xflag[0] & xflag[1] & xflag[2] & xflag[3])) break;
;         *(uint4*)(sK + so0) = rk0; *(uint4*)(sK + so1) = rk1; *(uint4*)(sV + so0) = rv0; *(uint4*)(sV + so1) = rv1;
;         if (!SB && t < 64) sF[t] = rf * LOG2E;
;         __syncthreads();
;         if (kt > 0) {
;             const size_t kb = (size_t)(kt - 1) * 64;
;             const bf16_t* kp = Kp + (kb + srow) * ldk + sch * 8; rk0 = *(const uint4*)kp; rk1 = *(const uint4*)(kp + 8);
;             const bf16_t* vp = VT + (size_t)srow * ldvt + kb + sch * 8; rv0 = *(const uint4*)vp; rv1 = *(const uint4*)(vp + 8);
;             if (!SB && t < 64) rf = Fk[kb + t];
;         }
.LBB0_1691:
	v_mov_b32_e32 v66, 0x4100
	s_waitcnt vmcnt(0) lgkmcnt(0)
	s_barrier
	ds_read_b128 v[66:69], v66
	s_or_b64 s[34:35], s[34:35], exec
	s_waitcnt lgkmcnt(0)
	v_and_b32_e32 v68, v66, v68
	v_bitop3_b32 v66, v68, v67, v69 bitop3:0x80
	v_cmp_eq_u32_e64 s[0:1], 0, v66
	s_and_saveexec_b64 s[38:39], s[0:1]
	s_cbranch_execz .LBB0_1690
	v_readlane_b32 s92, v252, 27
	v_readlane_b32 s93, v252, 28
	s_cmp_eq_u32 s92, -1
	ds_write_b128 v173, v[16:19]
	ds_write_b128 v174, v[20:23]
	ds_write_b128 v173, v[24:27] offset:8192
	ds_write_b128 v174, v[28:31] offset:8192
	s_waitcnt lgkmcnt(0)
	s_barrier
	s_cbranch_scc1 .LBB0_1694
	s_lshl_b64 s[0:1], s[92:93], 6
	v_lshl_add_u64 v[16:17], s[0:1], 0, v[100:101]
	v_lshlrev_b64 v[16:17], 9, v[16:17]
	s_lshl_b64 s[0:1], s[92:93], 7
	v_lshl_add_u64 v[20:21], v[102:103], 0, v[16:17]
	v_lshl_add_u64 v[28:29], v[104:105], 0, s[0:1]
	flat_load_dwordx4 v[16:19], v[20:21]
	s_nop 0
	flat_load_dwordx4 v[20:23], v[20:21] offset:16
	s_nop 0
	flat_load_dwordx4 v[24:27], v[28:29]
	s_nop 0
	flat_load_dwordx4 v[28:31], v[28:29] offset:16

; template <bool SB> ...
;     ...
;         if (early) {
;             int pred;
;             if (!SB) {
;                 const float f0 = sF[0];
;                 pred = (!rvalid[0] || (qkb * LOG2E + fqv[0] - f0 < m[0] - 104.f * LOG2E)) && (!rvalid[1] || (qkb * LOG2E + fqv[1] - f0 < m[1] - 104.f * LOG2E));
;             } else {
;                 pred = (!rvalid[0] || ls[0] == 0.f) && (!rvalid[1] || ls[1] == 0.f);
;             }
;             const int wall = __all(pred);
;             if (lane == 0) xflag[wid] = wall;
;         }
.LBB0_1696:
	s_or_b64 exec, exec, s[4:5]
	v_cmp_eq_f32_e32 vcc, 0, v109
	s_or_b64 s[0:1], s[40:41], vcc
	v_cmp_eq_f32_e32 vcc, 0, v108
	s_or_b64 s[4:5], s[12:13], vcc
	s_and_b64 s[0:1], s[0:1], s[4:5]
	v_cndmask_b32_e64 v66, 0, 1, s[0:1]
	v_cmp_ne_u32_e64 s[0:1], 0, v66
	s_mov_b64 s[4:5], exec
	s_and_saveexec_b64 s[6:7], s[42:43]
	s_cbranch_execz .LBB0_1689
	s_cmp_eq_u64 s[0:1], s[4:5]
	s_cselect_b64 s[0:1], -1, 0
	v_cndmask_b32_e64 v66, 0, 1, s[0:1]
	ds_write_b32 v106, v66
	s_waitcnt lgkmcnt(0)
	s_branch .LBB0_1689

; DEV int tid_opaque() { int t = threadIdx.x; asm volatile("" : "+v"(t)); return t; }
; template <bool SB> ...
;     const int t = tid_opaque(), lane = t & 63, wid = t >> 6, fr = lane & 15, fq = lane >> 4;
;     char* sK = smem; char* sV = smem + 8192; float* sF = (float*)(smem + 16384);
;     const int qw0 = wid * 32;
;     const bool wave_valid = qw0 < nq;
;     bf16x8 qf[2][2]; int kmax[2]; float fqv[2]; bool rvalid[2];
; #pragma unroll
;     for (int qt = 0; qt < 2; ++qt) {
;         const int qi = qw0 + qt * 16 + fr, qc = min(qi, nq - 1);
; #pragma unroll
;         for (int kk = 0; kk < 2; ++kk) qf[qt][kk] = *(const bf16x8*)(Q + (size_t)qc * ldq + kk * 32 + fq * 8);
;         rvalid[qt] = qi < nq;
;         kmax[qt] = rvalid[qt] ? q_pos0 + qi - (SB ? 1 : 0) : -1;
;         fqv[qt] = SB ? 0.f : Fq[qc] * LOG2E;
;     }
;     const int wave_kmax = wave_valid ? q_pos0 + min(qw0 + 31, nq - 1) - (SB ? 1 : 0) : -1;
;     const int kt_hi = (q_pos0 + nq - 1) >> 6;
;     f32x4 o[4][2];
; #pragma unroll
;     for (int a = 0; a < 4; ++a) { o[a][0] = (f32x4){0.f, 0.f, 0.f, 0.f}; o[a][1] = (f32x4){0.f, 0.f, 0.f, 0.f}; }
;     float m[2] = {-1e30f, -1e30f}, ls[2] = {SB ? 1.f : 0.f, SB ? 1.f : 0.f};
;     const int srow = t >> 2, sch = (t & 3) * 2;
;     uint4 rk0, rk1, rv0, rv1; float rf = 0.f;
;     {
;         const size_t kb = (size_t)kt_hi * 64;
;         const bf16_t* kp = Kp + (kb + srow) * ldk + sch * 8; rk0 = *(const uint4*)kp; rk1 = *(const uint4*)(kp + 8);
;         const bf16_t* vp = VT + (size_t)srow * ldvt + kb + sch * 8; rv0 = *(const uint4*)vp; rv1 = *(const uint4*)(vp + 8);
;         if (!SB && t < 64) rf = Fk[kb + t];
;     }
;     const int so0 = srow * 128 + ((sch ^ (srow & 7)) << 4), so1 = srow * 128 + (((sch + 1) ^ (srow & 7)) << 4);
;     const int sw = fr & 7;
;     volatile int* xflag = (volatile int*)(smem + 16384 + 256);
;     if (t < 4) xflag[t] = 0;
.LBB0_1720:
	v_readlane_b32 s2, v250, 52
	s_lshl_b32 s4, s2, 6
	s_ashr_i32 s5, s4, 31
	s_lshl_b64 s[4:5], s[4:5], 1
	s_add_u32 s12, s6, s4
	s_addc_u32 s13, s7, s5
	s_mul_i32 s6, s17, 0x180
	s_mul_hi_u32 s7, s16, 0x180
	s_add_i32 s7, s7, s6
	s_mul_i32 s6, s16, 0x180
	s_lshl_b64 s[6:7], s[6:7], 1
	v_readlane_b32 s2, v250, 5
	s_add_u32 s16, s2, s6
	v_readlane_b32 s2, v250, 6
	v_mov_b32_e32 v0, v186
	s_addc_u32 s17, s2, s7
	s_add_u32 s16, s16, s4
	v_ashrrev_i32_e32 v6, 6, v0
	v_and_b32_e32 v8, 15, v0
	v_lshlrev_b32_e32 v9, 5, v6
	s_addc_u32 s17, s17, s5
	v_or_b32_e32 v168, v9, v8
	s_add_i32 s18, s15, -1
	v_and_b32_e32 v32, 48, v0
	v_lshl_add_u64 v[2:3], s[16:17], 0, v[32:33]
	v_min_i32_e32 v4, s18, v168
	s_movk_i32 s19, 0x300
	v_mad_i64_i32 v[10:11], s[16:17], v4, s19, v[2:3]
	v_or_b32_e32 v155, 16, v168
	v_ashrrev_i32_e32 v5, 31, v4
	flat_load_dwordx4 v[34:37], v[10:11]
	flat_load_dwordx4 v[38:41], v[10:11] offset:64
	v_min_i32_e32 v10, s18, v155
	v_lshl_add_u64 v[4:5], v[4:5], 2, s[10:11]
	v_ashrrev_i32_e32 v11, 31, v10
	v_mad_i64_i32 v[2:3], s[16:17], v10, s19, v[2:3]
	flat_load_dword v5, v[4:5]
	s_nop 0
	flat_load_dwordx4 v[42:45], v[2:3]
	flat_load_dwordx4 v[46:49], v[2:3] offset:64
	v_lshl_add_u64 v[2:3], v[10:11], 2, s[10:11]
	s_add_i32 s10, s18, s46
	s_ashr_i32 s10, s10, 6
	v_ashrrev_i32_e32 v158, 2, v0
	s_ashr_i32 s11, s10, 31
	s_lshl_b64 s[16:17], s[10:11], 6
	v_ashrrev_i32_e32 v159, 31, v158
	flat_load_dword v7, v[2:3]
	v_lshlrev_b32_e32 v1, 1, v0
	v_lshl_add_u64 v[2:3], s[16:17], 0, v[158:159]
	v_mov_b64_e32 v[12:13], s[12:13]
	v_and_b32_e32 v10, 6, v1
	v_mad_u64_u32 v[12:13], s[20:21], v2, s19, v[12:13]
	v_mad_i32_i24 v13, v3, s19, v13
	v_lshlrev_b32_e32 v14, 4, v10
	v_mov_b32_e32 v15, v33
	v_lshl_add_u64 v[2:3], v[12:13], 0, v[14:15]
	flat_load_dwordx4 v[62:65], v[2:3]
	flat_load_dwordx4 v[66:69], v[2:3] offset:16
	v_mad_i64_i32 v[2:3], s[20:21], s14, v158, 0
	v_lshl_add_u64 v[2:3], v[2:3], 1, s[8:9]
	s_lshl_b64 s[8:9], s[10:11], 7
	v_lshl_add_u64 v[12:13], v[2:3], 0, s[8:9]
	v_lshl_add_u64 v[12:13], v[12:13], 0, v[14:15]
	flat_load_dwordx4 v[70:73], v[12:13]
	flat_load_dwordx4 v[74:77], v[12:13] offset:16
	v_cmp_gt_i32_e64 s[42:43], 64, v0
	v_mov_b32_e32 v170, 0
	v_ashrrev_i32_e32 v1, 31, v0
	v_readlane_b32 s3, v250, 53
	s_and_saveexec_b64 s[8:9], s[42:43]
	s_cbranch_execz .LBB0_1722
	s_lshl_b64 s[16:17], s[16:17], 2
	s_add_u32 s16, s0, s16
	s_addc_u32 s17, s1, s17
	v_lshl_add_u64 v[12:13], v[0:1], 2, s[16:17]
	flat_load_dword v170, v[12:13]
.LBB0_1722:
	s_or_b64 exec, exec, s[8:9]
	v_cmp_gt_i32_e32 vcc, 4, v0
	v_lshl_add_u32 v171, v0, 2, 0
	s_and_saveexec_b64 s[8:9], vcc
	s_cbranch_execz .LBB0_1724
	s_mov_b64 s[16:17], src_shared_base
	v_add_u32_e32 v12, 0x4100, v171
	v_mov_b32_e32 v13, s17
	ds_write_b32 v12, v33
	s_waitcnt vmcnt(0) lgkmcnt(0)

; template <bool SB> ...
;     ...
;         __syncthreads();
;         if (early && (xflag[0] & xflag[1] & xflag[2] & xflag[3])) break;
;         *(uint4*)(sK + so0) = rk0; *(uint4*)(sK + so1) = rk1; *(uint4*)(sV + so0) = rv0; *(uint4*)(sV + so1) = rv1;
;         if (!SB && t < 64) sF[t] = rf * LOG2E;
;         __syncthreads();
.LBB0_1731:
	v_cndmask_b32_e64 v0, 0, 1, s[26:27]
	v_cmp_ne_u32_e64 s[48:49], 1, v0
	s_andn2_b64 vcc, exec, s[26:27]
	s_mov_b64 s[16:17], s[56:57]
	s_barrier
	s_cbranch_vccnz .LBB0_1733
	v_mov_b32_e32 v0, 0x4100
	ds_read_b128 v[0:3], v0
	s_andn2_b64 s[0:1], s[56:57], exec
	s_waitcnt lgkmcnt(0)
	v_and_b32_e32 v2, v0, v2
	v_bitop3_b32 v0, v2, v1, v3 bitop3:0x80
	v_cmp_eq_u32_e32 vcc, 0, v0
	s_and_b64 s[14:15], vcc, exec
	s_or_b64 s[16:17], s[0:1], s[14:15]

; template <bool SB> ...
;     ...
;     f32x4 o[4][2];
; #pragma unroll
;     for (int a = 0; a < 4; ++a) { o[a][0] = (f32x4){0.f, 0.f, 0.f, 0.f}; o[a][1] = (f32x4){0.f, 0.f, 0.f, 0.f}; }
;     float m[2] = {-1e30f, -1e30f}, ls[2] = {SB ? 1.f : 0.f, SB ? 1.f : 0.f};
;     ...
;         if (early) {
;             int pred;
;             if (!SB) {
;                 const float f0 = sF[0];
;                 pred = (!rvalid[0] || (qkb * LOG2E + fqv[0] - f0 < m[0] - 104.f * LOG2E)) && (!rvalid[1] || (qkb * LOG2E + fqv[1] - f0 < m[1] - 104.f * LOG2E));
;             } else {
;                 pred = (!rvalid[0] || ls[0] == 0.f) && (!rvalid[1] || ls[1] == 0.f);
;             }
;             const int wall = __all(pred);
;             if (lane == 0) xflag[wid] = wall;
;         }
.LBB0_1758:
	s_or_b64 exec, exec, s[0:1]
	s_and_b64 vcc, exec, s[48:49]
	s_cbranch_vccnz .LBB0_1729
	s_mov_b64 s[0:1], -1
	s_and_saveexec_b64 s[16:17], s[40:41]
	s_cbranch_execz .LBB0_1761
	ds_read_b32 v0, v33 offset:16384
	v_add_f32_e32 v1, 0xc3160a50, v213
	v_add_f32_e32 v2, 0xc3160a50, v212
	s_waitcnt lgkmcnt(0)
	v_sub_f32_e32 v3, v178, v0
	v_sub_f32_e32 v0, v179, v0
	v_cmp_lt_f32_e64 s[0:1], v3, v1
	v_cmp_nlt_f32_e32 vcc, v3, v1
	s_or_b64 vcc, s[44:45], vcc
	v_cndmask_b32_e64 v1, 0, 1, s[0:1]
	v_cmp_lt_f32_e64 s[0:1], v0, v2
	s_nop 1
	v_cndmask_b32_e64 v0, 0, 1, s[0:1]
	v_cndmask_b32_e32 v0, v0, v1, vcc
	v_and_b32_e32 v0, 1, v0
	v_cmp_eq_u32_e32 vcc, 1, v0
	s_orn2_b64 s[0:1], vcc, exec
.LBB0_1761:
	s_or_b64 exec, exec, s[16:17]
	v_cndmask_b32_e64 v0, 0, 1, s[0:1]
	s_mov_b64 s[16:17], exec
	v_cmp_ne_u32_e32 vcc, 0, v0
	s_and_saveexec_b64 s[0:1], s[46:47]
	s_cbranch_execz .LBB0_1728
	s_cmp_eq_u64 vcc, s[16:17]
	s_cselect_b64 s[16:17], -1, 0
	v_cndmask_b32_e64 v0, 0, 1, s[16:17]
	ds_write_b32 v166, v0
	s_waitcnt lgkmcnt(0)
	s_branch .LBB0_1728
.LBB0_1763:
	s_waitcnt vmcnt(0) lgkmcnt(0)
	v_mov_b32_e32 v34, v33
	v_mov_b32_e32 v35, v33
	v_mov_b32_e32 v32, v33
	v_mov_b64_e32 v[52:53], v[34:35]
	v_mov_b64_e32 v[84:85], v[34:35]
	v_mov_b64_e32 v[60:61], v[34:35]
	v_mov_b64_e32 v[92:93], v[34:35]
	v_mov_b64_e32 v[102:103], v[34:35]
	v_mov_b64_e32 v[80:81], v[34:35]
	v_mov_b64_e32 v[88:89], v[34:35]
	v_mov_b64_e32 v[56:57], v[34:35]
	v_mov_b32_e32 v175, 0
	v_mov_b64_e32 v[50:51], v[32:33]
	v_mov_b64_e32 v[82:83], v[32:33]
	v_mov_b64_e32 v[58:59], v[32:33]
	v_mov_b64_e32 v[90:91], v[32:33]
	v_mov_b32_e32 v169, 0
	v_mov_b64_e32 v[100:101], v[32:33]
	v_mov_b64_e32 v[78:79], v[32:33]
	v_mov_b64_e32 v[86:87], v[32:33]
	v_mov_b64_e32 v[54:55], v[32:33]
	s_branch .LBB0_1765
